# previous + P0a modulation GEMV: the wave's 128 weight rows are touched into L2 before the 16-deep load rounds
# baseline (speedup 1.0000x reference)
; __device__ __forceinline__ void phase_p0a(const Args& a, LAS unsigned char* lds, int bid, int G, int wave) {
;     ...
;         for (int it = bid; it < 288; it += G) {
;             const int l = it / 144, n0 = (it % 144) * 64;
;             const float* W = a.ada_w + (size_t)l * D * NMOD + n0 + lane;
;             float acc[NBATCH];
; #pragma unroll
;             for (int b = 0; b < NBATCH; ++b) acc[b] = 0.f;
; #pragma unroll 16
;             for (int kk = 0; kk < 128; ++kk) { const int k = wave * 128 + kk; const float w = W[(size_t)k * NMOD];
.LBB0_20:
	s_mul_hi_i32 s0, s30, 0x38e38e39
	s_lshr_b32 s1, s0, 31
	s_ashr_i32 s0, s0, 5
	s_add_i32 s8, s0, s1
	s_mul_i32 s0, s8, 0x90
	s_sub_i32 s0, s30, s0
	s_lshl_b32 s0, s0, 6
	s_ashr_i32 s1, s0, 31
	s_mul_i32 s7, s8, 0x2400000
	s_lshl_b64 s[4:5], s[0:1], 2
	s_mul_hi_i32 s6, s8, 0x2400000
	s_add_u32 s0, s7, s4
	s_addc_u32 s1, s6, s5
	v_lshl_add_u64 v[12:13], v[10:11], 0, s[0:1]
	s_mov_b64 s[6:7], 0
	s_mov_b32 s9, s11
	v_mov_b32_e32 v14, 0
	v_mov_b32_e32 v15, v7
	v_mov_b32_e32 v16, 0
	v_mov_b32_e32 v17, v7
	v_mov_b32_e32 v18, 0
	v_mov_b32_e32 v19, v7
	v_mov_b32_e32 v20, 0
	v_mov_b32_e32 v21, v7
	v_mov_b32_e32 v22, 0
	v_mov_b32_e32 v23, v7
	v_mov_b32_e32 v220, v12
	v_mov_b32_e32 v221, v13
	s_mov_b32 s0, 0x9000
	s_mov_b32 s1, 0
	global_load_dword v222, v[220:221], off
	v_lshl_add_u64 v[220:221], v[220:221], 0, s[0:1]
	global_load_dword v222, v[220:221], off
	v_lshl_add_u64 v[220:221], v[220:221], 0, s[0:1]
	global_load_dword v222, v[220:221], off
	v_lshl_add_u64 v[220:221], v[220:221], 0, s[0:1]
	global_load_dword v222, v[220:221], off
	v_lshl_add_u64 v[220:221], v[220:221], 0, s[0:1]
	global_load_dword v222, v[220:221], off
	v_lshl_add_u64 v[220:221], v[220:221], 0, s[0:1]
	global_load_dword v222, v[220:221], off
	v_lshl_add_u64 v[220:221], v[220:221], 0, s[0:1]
	global_load_dword v222, v[220:221], off
	v_lshl_add_u64 v[220:221], v[220:221], 0, s[0:1]
	global_load_dword v222, v[220:221], off
	v_lshl_add_u64 v[220:221], v[220:221], 0, s[0:1]
	global_load_dword v222, v[220:221], off
	v_lshl_add_u64 v[220:221], v[220:221], 0, s[0:1]
	global_load_dword v222, v[220:221], off
	v_lshl_add_u64 v[220:221], v[220:221], 0, s[0:1]
	global_load_dword v222, v[220:221], off
	v_lshl_add_u64 v[220:221], v[220:221], 0, s[0:1]
	global_load_dword v222, v[220:221], off
	v_lshl_add_u64 v[220:221], v[220:221], 0, s[0:1]
	global_load_dword v222, v[220:221], off
	v_lshl_add_u64 v[220:221], v[220:221], 0, s[0:1]
	global_load_dword v222, v[220:221], off
	v_lshl_add_u64 v[220:221], v[220:221], 0, s[0:1]
	global_load_dword v222, v[220:221], off
	v_lshl_add_u64 v[220:221], v[220:221], 0, s[0:1]
	global_load_dword v222, v[220:221], off
	v_lshl_add_u64 v[220:221], v[220:221], 0, s[0:1]
	global_load_dword v222, v[220:221], off
	v_lshl_add_u64 v[220:221], v[220:221], 0, s[0:1]
	global_load_dword v222, v[220:221], off
	v_lshl_add_u64 v[220:221], v[220:221], 0, s[0:1]
	global_load_dword v222, v[220:221], off
	v_lshl_add_u64 v[220:221], v[220:221], 0, s[0:1]
	global_load_dword v222, v[220:221], off
	v_lshl_add_u64 v[220:221], v[220:221], 0, s[0:1]
	global_load_dword v222, v[220:221], off
	v_lshl_add_u64 v[220:221], v[220:221], 0, s[0:1]
	global_load_dword v222, v[220:221], off
	v_lshl_add_u64 v[220:221], v[220:221], 0, s[0:1]
	global_load_dword v222, v[220:221], off
	v_lshl_add_u64 v[220:221], v[220:221], 0, s[0:1]
	global_load_dword v222, v[220:221], off
	v_lshl_add_u64 v[220:221], v[220:221], 0, s[0:1]
	global_load_dword v222, v[220:221], off
	v_lshl_add_u64 v[220:221], v[220:221], 0, s[0:1]
	global_load_dword v222, v[220:221], off
	v_lshl_add_u64 v[220:221], v[220:221], 0, s[0:1]
	global_load_dword v222, v[220:221], off
	v_lshl_add_u64 v[220:221], v[220:221], 0, s[0:1]
	global_load_dword v222, v[220:221], off
	v_lshl_add_u64 v[220:221], v[220:221], 0, s[0:1]
	global_load_dword v222, v[220:221], off
	v_lshl_add_u64 v[220:221], v[220:221], 0, s[0:1]
	global_load_dword v222, v[220:221], off
	v_lshl_add_u64 v[220:221], v[220:221], 0, s[0:1]
	global_load_dword v222, v[220:221], off
	v_lshl_add_u64 v[220:221], v[220:221], 0, s[0:1]
	global_load_dword v222, v[220:221], off
	v_lshl_add_u64 v[220:221], v[220:221], 0, s[0:1]
	global_load_dword v222, v[220:221], off
	v_lshl_add_u64 v[220:221], v[220:221], 0, s[0:1]
	global_load_dword v222, v[220:221], off
	v_lshl_add_u64 v[220:221], v[220:221], 0, s[0:1]
	global_load_dword v222, v[220:221], off
	v_lshl_add_u64 v[220:221], v[220:221], 0, s[0:1]
	global_load_dword v222, v[220:221], off
	v_lshl_add_u64 v[220:221], v[220:221], 0, s[0:1]
	global_load_dword v222, v[220:221], off
	v_lshl_add_u64 v[220:221], v[220:221], 0, s[0:1]
	global_load_dword v222, v[220:221], off
	v_lshl_add_u64 v[220:221], v[220:221], 0, s[0:1]
	global_load_dword v222, v[220:221], off
	v_lshl_add_u64 v[220:221], v[220:221], 0, s[0:1]
	global_load_dword v222, v[220:221], off
	v_lshl_add_u64 v[220:221], v[220:221], 0, s[0:1]
	global_load_dword v222, v[220:221], off
	v_lshl_add_u64 v[220:221], v[220:221], 0, s[0:1]
	global_load_dword v222, v[220:221], off
	v_lshl_add_u64 v[220:221], v[220:221], 0, s[0:1]
	global_load_dword v222, v[220:221], off
	v_lshl_add_u64 v[220:221], v[220:221], 0, s[0:1]
	global_load_dword v222, v[220:221], off
	v_lshl_add_u64 v[220:221], v[220:221], 0, s[0:1]
	global_load_dword v222, v[220:221], off
	v_lshl_add_u64 v[220:221], v[220:221], 0, s[0:1]
	global_load_dword v222, v[220:221], off
	v_lshl_add_u64 v[220:221], v[220:221], 0, s[0:1]
	global_load_dword v222, v[220:221], off
	v_lshl_add_u64 v[220:221], v[220:221], 0, s[0:1]
	global_load_dword v222, v[220:221], off
	v_lshl_add_u64 v[220:221], v[220:221], 0, s[0:1]
	global_load_dword v222, v[220:221], off
	v_lshl_add_u64 v[220:221], v[220:221], 0, s[0:1]
	global_load_dword v222, v[220:221], off
	v_lshl_add_u64 v[220:221], v[220:221], 0, s[0:1]
	global_load_dword v222, v[220:221], off
	v_lshl_add_u64 v[220:221], v[220:221], 0, s[0:1]
	global_load_dword v222, v[220:221], off
	v_lshl_add_u64 v[220:221], v[220:221], 0, s[0:1]
	global_load_dword v222, v[220:221], off
	v_lshl_add_u64 v[220:221], v[220:221], 0, s[0:1]
	global_load_dword v222, v[220:221], off
	v_lshl_add_u64 v[220:221], v[220:221], 0, s[0:1]
; __device__ __forceinline__ void phase_p0a(const Args& a, LAS unsigned char* lds, int bid, int G, int wave) {
;     ...
;             for (int kk = 0; kk < 128; ++kk) { const int k = wave * 128 + kk; const float w = W[(size_t)k * NMOD];
	global_load_dword v222, v[220:221], off
	v_lshl_add_u64 v[220:221], v[220:221], 0, s[0:1]
	global_load_dword v222, v[220:221], off
	v_lshl_add_u64 v[220:221], v[220:221], 0, s[0:1]
	global_load_dword v222, v[220:221], off
	v_lshl_add_u64 v[220:221], v[220:221], 0, s[0:1]
	global_load_dword v222, v[220:221], off
	v_lshl_add_u64 v[220:221], v[220:221], 0, s[0:1]
	global_load_dword v222, v[220:221], off
	v_lshl_add_u64 v[220:221], v[220:221], 0, s[0:1]
	global_load_dword v222, v[220:221], off
	v_lshl_add_u64 v[220:221], v[220:221], 0, s[0:1]
	global_load_dword v222, v[220:221], off
	v_lshl_add_u64 v[220:221], v[220:221], 0, s[0:1]
	global_load_dword v222, v[220:221], off
	v_lshl_add_u64 v[220:221], v[220:221], 0, s[0:1]
	global_load_dword v222, v[220:221], off
	v_lshl_add_u64 v[220:221], v[220:221], 0, s[0:1]
	global_load_dword v222, v[220:221], off
	v_lshl_add_u64 v[220:221], v[220:221], 0, s[0:1]
	global_load_dword v222, v[220:221], off
	v_lshl_add_u64 v[220:221], v[220:221], 0, s[0:1]
	global_load_dword v222, v[220:221], off
	v_lshl_add_u64 v[220:221], v[220:221], 0, s[0:1]
	global_load_dword v222, v[220:221], off
	v_lshl_add_u64 v[220:221], v[220:221], 0, s[0:1]
	global_load_dword v222, v[220:221], off
	v_lshl_add_u64 v[220:221], v[220:221], 0, s[0:1]
	global_load_dword v222, v[220:221], off
	v_lshl_add_u64 v[220:221], v[220:221], 0, s[0:1]
	global_load_dword v222, v[220:221], off
	v_lshl_add_u64 v[220:221], v[220:221], 0, s[0:1]
	global_load_dword v222, v[220:221], off
	v_lshl_add_u64 v[220:221], v[220:221], 0, s[0:1]
	global_load_dword v222, v[220:221], off
	v_lshl_add_u64 v[220:221], v[220:221], 0, s[0:1]
	global_load_dword v222, v[220:221], off
	v_lshl_add_u64 v[220:221], v[220:221], 0, s[0:1]
	global_load_dword v222, v[220:221], off
	v_lshl_add_u64 v[220:221], v[220:221], 0, s[0:1]
	global_load_dword v222, v[220:221], off
	v_lshl_add_u64 v[220:221], v[220:221], 0, s[0:1]
	global_load_dword v222, v[220:221], off
	v_lshl_add_u64 v[220:221], v[220:221], 0, s[0:1]
	global_load_dword v222, v[220:221], off
	v_lshl_add_u64 v[220:221], v[220:221], 0, s[0:1]
	global_load_dword v222, v[220:221], off
	v_lshl_add_u64 v[220:221], v[220:221], 0, s[0:1]
	global_load_dword v222, v[220:221], off
	v_lshl_add_u64 v[220:221], v[220:221], 0, s[0:1]
	global_load_dword v222, v[220:221], off
	v_lshl_add_u64 v[220:221], v[220:221], 0, s[0:1]
	global_load_dword v222, v[220:221], off
	v_lshl_add_u64 v[220:221], v[220:221], 0, s[0:1]
	global_load_dword v222, v[220:221], off
	v_lshl_add_u64 v[220:221], v[220:221], 0, s[0:1]
	global_load_dword v222, v[220:221], off
	v_lshl_add_u64 v[220:221], v[220:221], 0, s[0:1]
	global_load_dword v222, v[220:221], off
	v_lshl_add_u64 v[220:221], v[220:221], 0, s[0:1]
	global_load_dword v222, v[220:221], off
	v_lshl_add_u64 v[220:221], v[220:221], 0, s[0:1]
	global_load_dword v222, v[220:221], off
	v_lshl_add_u64 v[220:221], v[220:221], 0, s[0:1]
	global_load_dword v222, v[220:221], off
	v_lshl_add_u64 v[220:221], v[220:221], 0, s[0:1]
	global_load_dword v222, v[220:221], off
	v_lshl_add_u64 v[220:221], v[220:221], 0, s[0:1]
	global_load_dword v222, v[220:221], off
	v_lshl_add_u64 v[220:221], v[220:221], 0, s[0:1]
	global_load_dword v222, v[220:221], off
	v_lshl_add_u64 v[220:221], v[220:221], 0, s[0:1]
	global_load_dword v222, v[220:221], off
	v_lshl_add_u64 v[220:221], v[220:221], 0, s[0:1]
	global_load_dword v222, v[220:221], off
	v_lshl_add_u64 v[220:221], v[220:221], 0, s[0:1]
	global_load_dword v222, v[220:221], off
	v_lshl_add_u64 v[220:221], v[220:221], 0, s[0:1]
	global_load_dword v222, v[220:221], off
	v_lshl_add_u64 v[220:221], v[220:221], 0, s[0:1]
	global_load_dword v222, v[220:221], off
	v_lshl_add_u64 v[220:221], v[220:221], 0, s[0:1]
	global_load_dword v222, v[220:221], off
	v_lshl_add_u64 v[220:221], v[220:221], 0, s[0:1]
	global_load_dword v222, v[220:221], off
	v_lshl_add_u64 v[220:221], v[220:221], 0, s[0:1]
	global_load_dword v222, v[220:221], off
	v_lshl_add_u64 v[220:221], v[220:221], 0, s[0:1]
	global_load_dword v222, v[220:221], off
	v_lshl_add_u64 v[220:221], v[220:221], 0, s[0:1]
	global_load_dword v222, v[220:221], off
	v_lshl_add_u64 v[220:221], v[220:221], 0, s[0:1]
	global_load_dword v222, v[220:221], off
	v_lshl_add_u64 v[220:221], v[220:221], 0, s[0:1]
	global_load_dword v222, v[220:221], off
	v_lshl_add_u64 v[220:221], v[220:221], 0, s[0:1]
	global_load_dword v222, v[220:221], off
	v_lshl_add_u64 v[220:221], v[220:221], 0, s[0:1]
	global_load_dword v222, v[220:221], off
	v_lshl_add_u64 v[220:221], v[220:221], 0, s[0:1]
	global_load_dword v222, v[220:221], off
	v_lshl_add_u64 v[220:221], v[220:221], 0, s[0:1]
	global_load_dword v222, v[220:221], off
	v_lshl_add_u64 v[220:221], v[220:221], 0, s[0:1]
	global_load_dword v222, v[220:221], off
	v_lshl_add_u64 v[220:221], v[220:221], 0, s[0:1]
	global_load_dword v222, v[220:221], off
	v_lshl_add_u64 v[220:221], v[220:221], 0, s[0:1]
	global_load_dword v222, v[220:221], off
	v_lshl_add_u64 v[220:221], v[220:221], 0, s[0:1]
	global_load_dword v222, v[220:221], off
	v_lshl_add_u64 v[220:221], v[220:221], 0, s[0:1]
	global_load_dword v222, v[220:221], off
	v_lshl_add_u64 v[220:221], v[220:221], 0, s[0:1]
	global_load_dword v222, v[220:221], off
	v_lshl_add_u64 v[220:221], v[220:221], 0, s[0:1]
	global_load_dword v222, v[220:221], off
	v_lshl_add_u64 v[220:221], v[220:221], 0, s[0:1]
	global_load_dword v222, v[220:221], off
	v_lshl_add_u64 v[220:221], v[220:221], 0, s[0:1]
	global_load_dword v222, v[220:221], off
	v_lshl_add_u64 v[220:221], v[220:221], 0, s[0:1]
	global_load_dword v222, v[220:221], off
	v_lshl_add_u64 v[220:221], v[220:221], 0, s[0:1]
	global_load_dword v222, v[220:221], off
	v_lshl_add_u64 v[220:221], v[220:221], 0, s[0:1]
	global_load_dword v222, v[220:221], off
	v_lshl_add_u64 v[220:221], v[220:221], 0, s[0:1]
	global_load_dword v222, v[220:221], off
	v_lshl_add_u64 v[220:221], v[220:221], 0, s[0:1]
	global_load_dword v222, v[220:221], off
	v_lshl_add_u64 v[220:221], v[220:221], 0, s[0:1]
	global_load_dword v222, v[220:221], off
	v_lshl_add_u64 v[220:221], v[220:221], 0, s[0:1]
	global_load_dword v222, v[220:221], off
	v_lshl_add_u64 v[220:221], v[220:221], 0, s[0:1]
	global_load_dword v222, v[220:221], off
	v_lshl_add_u64 v[220:221], v[220:221], 0, s[0:1]
	global_load_dword v222, v[220:221], off
	v_lshl_add_u64 v[220:221], v[220:221], 0, s[0:1]
	global_load_dword v222, v[220:221], off
	v_lshl_add_u64 v[220:221], v[220:221], 0, s[0:1]
	global_load_dword v222, v[220:221], off
	v_lshl_add_u64 v[220:221], v[220:221], 0, s[0:1]
	global_load_dword v222, v[220:221], off
	v_lshl_add_u64 v[220:221], v[220:221], 0, s[0:1]
	global_load_dword v222, v[220:221], off
